# adds to previous: P6/P8 residual epilogue requests both half-tiles of the residual up front (second half no longer queued behind the first half's stores)
# baseline (speedup 1.0000x reference)
; __device__ __forceinline__ unsigned cvt_pk_bf16(float lo, float hi) { unsigned r; asm volatile("v_cvt_pk_bf16_f32 %0, %1, %2" : "=v"(r) : "v"(lo), "v"(hi)); return r; }
; __device__ __forceinline__ float bflo(unsigned w) { return __uint_as_float(w << 16); }
; __device__ __forceinline__ float bfhi(unsigned w) { return __uint_as_float(w & 0xffff0000u); }
;     __device__ __forceinline__ void operator()(const f32x4 (&acc)[2][2][4][2], const Unit& u, int wr, int wc, int fr, int fq) const {
;         const int row0 = u.pm * BM + wr * 64 + fr, col0 = u.pn * BM + wc * 32 + 8 * fq;
; #pragma unroll
;         for (int ai = 0; ai < 2; ++ai) {
;             u32x4 bw[4][2];
; #pragma unroll
;             for (int m = 0; m < 4; ++m)
; #pragma unroll
;                 for (int bj = 0; bj < 2; ++bj) bw[m][bj] = *(const u32x4*)((const bf16_t*)base + (size_t)(row0 + ai * HALF + m * 16) * DM + col0 + bj * HALF);
; #pragma unroll
;             for (int m = 0; m < 4; ++m) { const int row = row0 + ai * HALF + m * 16; const size_t off = (size_t)row * DM + col0; float ss = 0.f;
; #pragma unroll
;                 for (int bj = 0; bj < 2; ++bj) { const u32x4 w = bw[m][bj];
;                     const f32x4 b0 = {bflo(w.x), bfhi(w.x), bflo(w.y), bfhi(w.y)}, b1 = {bflo(w.z), bfhi(w.z), bflo(w.w), bfhi(w.w)};
;                     const f32x4 o0 = b0 + acc[ai][bj][m][0], o1 = b1 + acc[ai][bj][m][1];
;                     ss += ((o0[0] * o0[0] + o0[1] * o0[1]) + (o0[2] * o0[2] + o0[3] * o0[3])) + ((o1[0] * o1[0] + o1[1] * o1[1]) + (o1[2] * o1[2] + o1[3] * o1[3]));
;                     u32x4 w2; w2.x = cvt_pk_bf16(o0[0], o0[1]); w2.y = cvt_pk_bf16(o0[2], o0[3]); w2.z = cvt_pk_bf16(o1[0], o1[1]); w2.w = cvt_pk_bf16(o1[2], o1[3]);
;                     *(u32x4*)(hout + off + bj * HALF) = w2; }
;                 ss += __shfl_xor(ss, 16); ss += __shfl_xor(ss, 32);
;                 if (fq == 0) part[(size_t)row * 64 + u.pn * 4 + wc] = ss; }
.LBB0_1099:
	v_lshl_or_b32 v170, s8, 8, v191
	v_lshl_add_u32 v174, s26, 8, v183
	v_ashrrev_i32_e32 v171, 31, v170
	v_lshlrev_b64 v[206:207], 1, v[170:171]
	v_ashrrev_i32_e32 v175, 31, v174
	v_lshl_add_u64 v[172:173], s[74:75], 0, v[206:207]
	v_lshlrev_b64 v[196:197], 13, v[174:175]
	v_lshl_add_u64 v[130:131], v[172:173], 0, v[196:197]
	global_load_dwordx4 v[198:201], v[130:131], off
	global_load_dwordx4 v[202:205], v[130:131], off offset:256
	v_or_b32_e32 v186, 16, v174
	v_or_b32_e32 v180, 32, v174
	v_or_b32_e32 v176, 48, v174
	v_ashrrev_i32_e32 v187, 31, v186
	v_ashrrev_i32_e32 v181, 31, v180
	v_ashrrev_i32_e32 v177, 31, v176
	v_lshlrev_b64 v[188:189], 13, v[186:187]
	v_lshlrev_b64 v[184:185], 13, v[180:181]
	v_lshlrev_b64 v[178:179], 13, v[176:177]
	v_lshl_add_u64 v[130:131], v[172:173], 0, v[188:189]
	v_lshl_add_u64 v[132:133], v[172:173], 0, v[184:185]
	v_lshl_add_u64 v[208:209], v[172:173], 0, v[178:179]
	global_load_dwordx4 v[150:153], v[130:131], off
	global_load_dwordx4 v[146:149], v[130:131], off offset:256
	global_load_dwordx4 v[142:145], v[132:133], off
	global_load_dwordx4 v[138:141], v[132:133], off offset:256
	global_load_dwordx4 v[134:137], v[208:209], off
	s_nop 0
	global_load_dwordx4 v[130:133], v[208:209], off offset:256
	v_add_u32_e32 v218, 0x80, v174
	v_ashrrev_i32_e32 v219, 31, v218
	v_lshlrev_b64 v[218:219], 13, v[218:219]
	v_lshl_add_u64 v[218:219], v[172:173], 0, v[218:219]
	global_load_dwordx4 v[220:223], v[218:219], off
	global_load_dwordx4 v[224:227], v[218:219], off offset:256
	v_add_co_u32_e32 v218, vcc, 0x20000, v218
	s_nop 1
	v_addc_co_u32_e32 v219, vcc, 0, v219, vcc
	global_load_dwordx4 v[228:231], v[218:219], off
	global_load_dwordx4 v[232:235], v[218:219], off offset:256
	v_add_co_u32_e32 v218, vcc, 0x20000, v218
	s_nop 1
	v_addc_co_u32_e32 v219, vcc, 0, v219, vcc
	global_load_dwordx4 v[236:239], v[218:219], off
	global_load_dwordx4 v[240:243], v[218:219], off offset:256
	v_add_co_u32_e32 v218, vcc, 0x20000, v218
	s_nop 1
	v_addc_co_u32_e32 v219, vcc, 0, v219, vcc
	global_load_dwordx4 v[244:247], v[218:219], off
	global_load_dwordx4 v[248:251], v[218:219], off offset:256
	v_and_b32_e32 v209, 64, v195
	v_xor_b32_e32 v208, 16, v195
	v_add_u32_e32 v209, 64, v209
	v_xor_b32_e32 v210, 32, v195
	v_cmp_lt_i32_e32 vcc, v208, v209
	s_lshl_b32 s26, s8, 2
	s_ashr_i32 s27, s26, 31
	v_cndmask_b32_e32 v211, v195, v208, vcc
	v_cmp_lt_i32_e32 vcc, v210, v209
	v_lshl_add_u64 v[208:209], s[74:75], 0, v[196:197]
	v_lshlrev_b32_e32 v196, 2, v211
	v_cndmask_b32_e32 v216, v195, v210, vcc
	v_lshl_add_u64 v[206:207], v[208:209], 0, v[206:207]
	s_waitcnt vmcnt(0)
	v_lshlrev_b32_e32 v208, 16, v198
	v_and_b32_e32 v209, 0xffff0000, v198
	v_lshlrev_b32_e32 v198, 16, v199
	v_and_b32_e32 v199, 0xffff0000, v199
	v_lshlrev_b32_e32 v210, 16, v200
	v_and_b32_e32 v211, 0xffff0000, v200
	v_lshlrev_b32_e32 v200, 16, v201
	v_and_b32_e32 v201, 0xffff0000, v201
	v_lshlrev_b32_e32 v212, 16, v202
	v_and_b32_e32 v213, 0xffff0000, v202
	v_lshlrev_b32_e32 v202, 16, v203
	v_and_b32_e32 v203, 0xffff0000, v203
	v_lshlrev_b32_e32 v214, 16, v204
	v_and_b32_e32 v215, 0xffff0000, v204
	v_lshlrev_b32_e32 v204, 16, v205
	v_and_b32_e32 v205, 0xffff0000, v205
	v_pk_add_f32 v[128:129], v[128:129], v[198:199]
	v_pk_add_f32 v[126:127], v[126:127], v[208:209]
	v_pk_add_f32 v[124:125], v[124:125], v[200:201]
	v_pk_add_f32 v[122:123], v[122:123], v[210:211]
	v_pk_add_f32 v[120:121], v[120:121], v[202:203]
	v_pk_add_f32 v[118:119], v[118:119], v[212:213]
	v_pk_add_f32 v[198:199], v[116:117], v[204:205]
	v_pk_add_f32 v[200:201], v[114:115], v[214:215]
	v_mul_f32_e32 v116, v127, v127
	v_mul_f32_e32 v117, v129, v129
	v_mul_f32_e32 v197, v123, v123
	v_mul_f32_e32 v202, v125, v125
	v_cvt_pk_bf16_f32 v114, v126, v127
	v_cvt_pk_bf16_f32 v115, v128, v129
	v_mul_f32_e32 v127, v119, v119
	v_mul_f32_e32 v129, v121, v121
	v_mul_f32_e32 v203, v201, v201
	v_mul_f32_e32 v204, v199, v199
	v_fmac_f32_e32 v116, v126, v126
	v_fmac_f32_e32 v117, v128, v128
	v_fmac_f32_e32 v197, v122, v122
	v_fmac_f32_e32 v202, v124, v124
	v_fmac_f32_e32 v127, v118, v118
	v_fmac_f32_e32 v129, v120, v120
	v_fmac_f32_e32 v203, v200, v200
	v_fmac_f32_e32 v204, v198, v198
	v_add_f32_e32 v116, v116, v117
	v_add_f32_e32 v117, v197, v202
	v_add_f32_e32 v126, v127, v129
	v_add_f32_e32 v127, v203, v204
	v_add_f32_e32 v116, v116, v117
	v_add_f32_e32 v117, v126, v127
	v_add_f32_e32 v126, v116, v117
	ds_bpermute_b32 v127, v196, v126
	v_cvt_pk_bf16_f32 v116, v122, v123
	v_cvt_pk_bf16_f32 v117, v124, v125
	global_store_dwordx4 v[206:207], v[114:117], off
	v_cvt_pk_bf16_f32 v118, v118, v119
	v_cvt_pk_bf16_f32 v119, v120, v121
	v_cvt_pk_bf16_f32 v120, v200, v201
	v_cvt_pk_bf16_f32 v121, v198, v199
	global_store_dwordx4 v[206:207], v[118:121], off offset:256
	s_waitcnt lgkmcnt(0)
	v_add_f32_e32 v115, v126, v127
	v_lshlrev_b32_e32 v114, 2, v216
	ds_bpermute_b32 v116, v114, v115
	s_and_saveexec_b64 s[28:29], s[4:5]
	s_cbranch_execz .LBB0_1101
	v_lshlrev_b64 v[118:119], 8, v[174:175]
	v_lshl_add_u64 v[118:119], s[10:11], 0, v[118:119]
	v_lshl_add_u64 v[118:119], s[26:27], 2, v[118:119]
	s_lshl_b32 s8, s39, 2
	v_lshl_add_u64 v[118:119], v[118:119], 0, s[8:9]
	s_waitcnt lgkmcnt(0)
	v_add_f32_e32 v115, v115, v116
	global_store_dword v[118:119], v115, off

; __device__ __forceinline__ unsigned cvt_pk_bf16(float lo, float hi) { unsigned r; asm volatile("v_cvt_pk_bf16_f32 %0, %1, %2" : "=v"(r) : "v"(lo), "v"(hi)); return r; }
; __device__ __forceinline__ float bflo(unsigned w) { return __uint_as_float(w << 16); }
; __device__ __forceinline__ float bfhi(unsigned w) { return __uint_as_float(w & 0xffff0000u); }
;     __device__ __forceinline__ void operator()(const f32x4 (&acc)[2][2][4][2], const Unit& u, int wr, int wc, int fr, int fq) const {
;     ...
;         for (int ai = 0; ai < 2; ++ai) {
;             u32x4 bw[4][2];
; #pragma unroll
;             for (int m = 0; m < 4; ++m)
; #pragma unroll
;                 for (int bj = 0; bj < 2; ++bj) bw[m][bj] = *(const u32x4*)((const bf16_t*)base + (size_t)(row0 + ai * HALF + m * 16) * DM + col0 + bj * HALF);
; #pragma unroll
;             for (int m = 0; m < 4; ++m) { const int row = row0 + ai * HALF + m * 16; const size_t off = (size_t)row * DM + col0; float ss = 0.f;
; #pragma unroll
;                 for (int bj = 0; bj < 2; ++bj) { const u32x4 w = bw[m][bj];
;                     const f32x4 b0 = {bflo(w.x), bfhi(w.x), bflo(w.y), bfhi(w.y)}, b1 = {bflo(w.z), bfhi(w.z), bflo(w.w), bfhi(w.w)};
;                     const f32x4 o0 = b0 + acc[ai][bj][m][0], o1 = b1 + acc[ai][bj][m][1];
;                     ss += ((o0[0] * o0[0] + o0[1] * o0[1]) + (o0[2] * o0[2] + o0[3] * o0[3])) + ((o1[0] * o1[0] + o1[1] * o1[1]) + (o1[2] * o1[2] + o1[3] * o1[3]));
;                     u32x4 w2; w2.x = cvt_pk_bf16(o0[0], o0[1]); w2.y = cvt_pk_bf16(o0[2], o0[3]); w2.z = cvt_pk_bf16(o1[0], o1[1]); w2.w = cvt_pk_bf16(o1[2], o1[3]);
;                     *(u32x4*)(hout + off + bj * HALF) = w2; }
;                 ss += __shfl_xor(ss, 16); ss += __shfl_xor(ss, 32);
;                 if (fq == 0) part[(size_t)row * 64 + u.pn * 4 + wc] = ss; }
.LBB0_1107:
	s_or_b64 exec, exec, s[28:29]
	v_add_u32_e32 v102, 0x80, v174
	v_ashrrev_i32_e32 v103, 31, v102
	v_lshlrev_b64 v[112:113], 13, v[102:103]
	s_waitcnt lgkmcnt(0)
	v_lshl_add_u64 v[66:67], v[172:173], 0, v[112:113]
	v_add_u32_e32 v98, 0x90, v174
	v_add_u32_e32 v94, 0xa0, v174
	v_add_u32_e32 v90, 0xb0, v174
	v_ashrrev_i32_e32 v99, 31, v98
	v_ashrrev_i32_e32 v95, 31, v94
	v_ashrrev_i32_e32 v91, 31, v90
	v_lshlrev_b64 v[100:101], 13, v[98:99]
	v_lshlrev_b64 v[96:97], 13, v[94:95]
	v_lshlrev_b64 v[92:93], 13, v[90:91]
	v_lshl_add_u64 v[66:67], v[172:173], 0, v[100:101]
	v_lshl_add_u64 v[68:69], v[172:173], 0, v[96:97]
	v_lshl_add_u64 v[116:117], v[172:173], 0, v[92:93]
	s_nop 0
	v_mov_b32_e32 v104, v220
	v_mov_b32_e32 v105, v221
	v_mov_b32_e32 v106, v222
	v_mov_b32_e32 v107, v223
	v_mov_b32_e32 v108, v224
	v_mov_b32_e32 v109, v225
	v_mov_b32_e32 v110, v226
	v_mov_b32_e32 v111, v227
	v_mov_b32_e32 v86, v228
	v_mov_b32_e32 v87, v229
	v_mov_b32_e32 v88, v230
	v_mov_b32_e32 v89, v231
	v_mov_b32_e32 v82, v232
	v_mov_b32_e32 v83, v233
	v_mov_b32_e32 v84, v234
	v_mov_b32_e32 v85, v235
	v_mov_b32_e32 v78, v236
	v_mov_b32_e32 v79, v237
	v_mov_b32_e32 v80, v238
	v_mov_b32_e32 v81, v239
	v_mov_b32_e32 v74, v240
	v_mov_b32_e32 v75, v241
	v_mov_b32_e32 v76, v242
	v_mov_b32_e32 v77, v243
	v_mov_b32_e32 v70, v244
	v_mov_b32_e32 v71, v245
	v_mov_b32_e32 v72, v246
	v_mov_b32_e32 v73, v247
	v_mov_b32_e32 v66, v248
	v_mov_b32_e32 v67, v249
	v_mov_b32_e32 v68, v250
	v_mov_b32_e32 v69, v251
	v_lshlrev_b32_e32 v116, 16, v104
	v_and_b32_e32 v117, 0xffff0000, v104
	v_lshlrev_b32_e32 v104, 16, v105
	v_and_b32_e32 v105, 0xffff0000, v105
	v_lshlrev_b32_e32 v118, 16, v106
	v_and_b32_e32 v119, 0xffff0000, v106
	v_lshlrev_b32_e32 v106, 16, v107
	v_and_b32_e32 v107, 0xffff0000, v107
	v_lshlrev_b32_e32 v120, 16, v108
	v_and_b32_e32 v121, 0xffff0000, v108
	v_lshlrev_b32_e32 v108, 16, v109
	v_and_b32_e32 v109, 0xffff0000, v109
	v_lshlrev_b32_e32 v122, 16, v110
	v_and_b32_e32 v123, 0xffff0000, v110
	v_lshlrev_b32_e32 v110, 16, v111
	v_and_b32_e32 v111, 0xffff0000, v111
	v_pk_add_f32 v[64:65], v[64:65], v[104:105]
	v_pk_add_f32 v[62:63], v[62:63], v[116:117]
	v_pk_add_f32 v[60:61], v[60:61], v[106:107]
	v_pk_add_f32 v[58:59], v[58:59], v[118:119]
	v_pk_add_f32 v[56:57], v[56:57], v[108:109]
	v_pk_add_f32 v[54:55], v[54:55], v[120:121]
	v_pk_add_f32 v[104:105], v[52:53], v[110:111]
	v_pk_add_f32 v[106:107], v[50:51], v[122:123]
	v_mul_f32_e32 v108, v63, v63
	v_mul_f32_e32 v109, v65, v65
	v_mul_f32_e32 v110, v59, v59
	v_mul_f32_e32 v111, v61, v61
	v_cvt_pk_bf16_f32 v50, v62, v63
	v_cvt_pk_bf16_f32 v51, v64, v65
	v_cvt_pk_bf16_f32 v52, v58, v59
	v_cvt_pk_bf16_f32 v53, v60, v61
	v_mul_f32_e32 v59, v55, v55
	v_mul_f32_e32 v61, v57, v57
	v_mul_f32_e32 v63, v107, v107
	v_mul_f32_e32 v65, v105, v105
	v_fmac_f32_e32 v108, v62, v62
	v_fmac_f32_e32 v109, v64, v64
	v_fmac_f32_e32 v110, v58, v58
	v_fmac_f32_e32 v111, v60, v60
	v_fmac_f32_e32 v59, v54, v54
	v_fmac_f32_e32 v61, v56, v56
	v_fmac_f32_e32 v63, v106, v106
	v_fmac_f32_e32 v65, v104, v104
	v_add_f32_e32 v58, v108, v109
	v_add_f32_e32 v60, v110, v111
	v_add_f32_e32 v59, v59, v61
	v_add_f32_e32 v61, v63, v65
	v_add_f32_e32 v58, v58, v60
	v_add_f32_e32 v59, v59, v61
	v_add_f32_e32 v60, v58, v59
	ds_bpermute_b32 v61, v196, v60
	v_lshl_add_u64 v[58:59], s[74:75], 0, v[112:113]
	v_lshl_add_u64 v[58:59], v[170:171], 1, v[58:59]
	global_store_dwordx4 v[58:59], v[50:53], off
	s_waitcnt lgkmcnt(0)
	s_nop 0
	v_add_f32_e32 v50, v60, v61
	ds_bpermute_b32 v51, v114, v50
	v_cvt_pk_bf16_f32 v52, v54, v55
	v_cvt_pk_bf16_f32 v53, v56, v57
	v_cvt_pk_bf16_f32 v54, v106, v107
	v_cvt_pk_bf16_f32 v55, v104, v105
	global_store_dwordx4 v[58:59], v[52:55], off offset:256
	s_and_saveexec_b64 s[28:29], s[4:5]
	s_cbranch_execz .LBB0_1109
	v_lshlrev_b64 v[52:53], 8, v[102:103]
	v_lshl_add_u64 v[52:53], s[10:11], 0, v[52:53]
	v_lshl_add_u64 v[52:53], s[26:27], 2, v[52:53]
	s_lshl_b32 s8, s39, 2
	v_lshl_add_u64 v[52:53], v[52:53], 0, s[8:9]
	s_waitcnt lgkmcnt(0)
	v_add_f32_e32 v50, v50, v51
	global_store_dword v[52:53], v50, off
.LBB0_1109:
	s_or_b64 exec, exec, s[28:29]
	v_lshlrev_b32_e32 v50, 16, v86
	s_waitcnt lgkmcnt(0)
	v_and_b32_e32 v51, 0xffff0000, v86
	v_lshlrev_b32_e32 v52, 16, v87
	v_and_b32_e32 v53, 0xffff0000, v87
	v_lshlrev_b32_e32 v54, 16, v88
	v_and_b32_e32 v55, 0xffff0000, v88
	v_lshlrev_b32_e32 v56, 16, v89
	v_and_b32_e32 v57, 0xffff0000, v89
	v_pk_add_f32 v[48:49], v[48:49], v[52:53]
	v_pk_add_f32 v[46:47], v[46:47], v[50:51]
	v_pk_add_f32 v[50:51], v[44:45], v[56:57]
	v_pk_add_f32 v[44:45], v[42:43], v[54:55]
	v_mul_f32_e32 v42, v47, v47
	v_mul_f32_e32 v43, v49, v49
	v_fmac_f32_e32 v42, v46, v46
	v_fmac_f32_e32 v43, v48, v48
	v_add_f32_e32 v42, v42, v43
	v_mul_f32_e32 v43, v45, v45
	v_mul_f32_e32 v52, v51, v51
	v_fmac_f32_e32 v43, v44, v44
	v_fmac_f32_e32 v52, v50, v50
	v_add_f32_e32 v43, v43, v52
	v_add_f32_e32 v54, v42, v43
	v_cvt_pk_bf16_f32 v42, v46, v47
	v_cvt_pk_bf16_f32 v43, v48, v49
	v_lshlrev_b32_e32 v46, 16, v82
	v_and_b32_e32 v47, 0xffff0000, v82
	v_lshlrev_b32_e32 v48, 16, v83
	v_and_b32_e32 v49, 0xffff0000, v83
	v_cvt_pk_bf16_f32 v44, v44, v45
	v_cvt_pk_bf16_f32 v45, v50, v51
	v_lshlrev_b32_e32 v50, 16, v84
	v_and_b32_e32 v51, 0xffff0000, v84
	v_pk_add_f32 v[40:41], v[40:41], v[48:49]
	v_pk_add_f32 v[38:39], v[38:39], v[46:47]
	v_lshlrev_b32_e32 v52, 16, v85
	v_and_b32_e32 v53, 0xffff0000, v85
	v_pk_add_f32 v[48:49], v[34:35], v[50:51]
	v_mul_f32_e32 v34, v39, v39
	v_mul_f32_e32 v35, v41, v41
	v_pk_add_f32 v[46:47], v[36:37], v[52:53]
	v_fmac_f32_e32 v34, v38, v38
	v_fmac_f32_e32 v35, v40, v40
	v_add_f32_e32 v34, v34, v35
	v_mul_f32_e32 v35, v49, v49
	v_mul_f32_e32 v36, v47, v47
	v_fmac_f32_e32 v35, v48, v48
	v_fmac_f32_e32 v36, v46, v46
	v_add_f32_e32 v35, v35, v36
	v_add_f32_e32 v34, v34, v35
	v_add_f32_e32 v37, v54, v34
	ds_bpermute_b32 v52, v196, v37
	v_lshl_add_u64 v[34:35], s[74:75], 0, v[100:101]
	v_lshl_add_u64 v[50:51], v[170:171], 1, v[34:35]
	global_store_dwordx4 v[50:51], v[42:45], off
	v_cvt_pk_bf16_f32 v36, v38, v39
	s_waitcnt lgkmcnt(0)
	v_add_f32_e32 v34, v37, v52
	ds_bpermute_b32 v35, v114, v34
	v_cvt_pk_bf16_f32 v37, v40, v41
	v_cvt_pk_bf16_f32 v38, v48, v49
	v_cvt_pk_bf16_f32 v39, v46, v47
	global_store_dwordx4 v[50:51], v[36:39], off offset:256
	s_and_saveexec_b64 s[28:29], s[4:5]
	s_cbranch_execz .LBB0_1111
	v_lshlrev_b64 v[36:37], 8, v[98:99]
	v_lshl_add_u64 v[36:37], s[10:11], 0, v[36:37]
	v_lshl_add_u64 v[36:37], s[26:27], 2, v[36:37]
	s_lshl_b32 s8, s39, 2
	v_lshl_add_u64 v[36:37], v[36:37], 0, s[8:9]
	s_waitcnt lgkmcnt(0)
	v_add_f32_e32 v34, v34, v35
	global_store_dword v[36:37], v34, off
; __device__ __forceinline__ unsigned cvt_pk_bf16(float lo, float hi) { unsigned r; asm volatile("v_cvt_pk_bf16_f32 %0, %1, %2" : "=v"(r) : "v"(lo), "v"(hi)); return r; }
; __device__ __forceinline__ float bflo(unsigned w) { return __uint_as_float(w << 16); }
; __device__ __forceinline__ float bfhi(unsigned w) { return __uint_as_float(w & 0xffff0000u); }
;     __device__ __forceinline__ void operator()(const f32x4 (&acc)[2][2][4][2], const Unit& u, int wr, int wc, int fr, int fq) const {
;     ...
;         for (int ai = 0; ai < 2; ++ai) {
;             u32x4 bw[4][2];
; #pragma unroll
;             for (int m = 0; m < 4; ++m)
; #pragma unroll
;                 for (int bj = 0; bj < 2; ++bj) bw[m][bj] = *(const u32x4*)((const bf16_t*)base + (size_t)(row0 + ai * HALF + m * 16) * DM + col0 + bj * HALF);
; #pragma unroll
;             for (int m = 0; m < 4; ++m) { const int row = row0 + ai * HALF + m * 16; const size_t off = (size_t)row * DM + col0; float ss = 0.f;
; #pragma unroll
;                 for (int bj = 0; bj < 2; ++bj) { const u32x4 w = bw[m][bj];
;                     const f32x4 b0 = {bflo(w.x), bfhi(w.x), bflo(w.y), bfhi(w.y)}, b1 = {bflo(w.z), bfhi(w.z), bflo(w.w), bfhi(w.w)};
;                     const f32x4 o0 = b0 + acc[ai][bj][m][0], o1 = b1 + acc[ai][bj][m][1];
;                     ss += ((o0[0] * o0[0] + o0[1] * o0[1]) + (o0[2] * o0[2] + o0[3] * o0[3])) + ((o1[0] * o1[0] + o1[1] * o1[1]) + (o1[2] * o1[2] + o1[3] * o1[3]));
;                     u32x4 w2; w2.x = cvt_pk_bf16(o0[0], o0[1]); w2.y = cvt_pk_bf16(o0[2], o0[3]); w2.z = cvt_pk_bf16(o1[0], o1[1]); w2.w = cvt_pk_bf16(o1[2], o1[3]);
;                     *(u32x4*)(hout + off + bj * HALF) = w2; }
;                 ss += __shfl_xor(ss, 16); ss += __shfl_xor(ss, 32);
;                 if (fq == 0) part[(size_t)row * 64 + u.pn * 4 + wc] = ss; }
.LBB0_1111:
	s_or_b64 exec, exec, s[28:29]
	v_lshlrev_b32_e32 v34, 16, v78
	s_waitcnt lgkmcnt(0)
	v_and_b32_e32 v35, 0xffff0000, v78
	v_lshlrev_b32_e32 v36, 16, v79
	v_and_b32_e32 v37, 0xffff0000, v79
	v_lshlrev_b32_e32 v38, 16, v80
	v_and_b32_e32 v39, 0xffff0000, v80
	v_lshlrev_b32_e32 v40, 16, v81
	v_and_b32_e32 v41, 0xffff0000, v81
	v_pk_add_f32 v[32:33], v[32:33], v[36:37]
	v_pk_add_f32 v[30:31], v[30:31], v[34:35]
	v_pk_add_f32 v[34:35], v[28:29], v[40:41]
	v_pk_add_f32 v[28:29], v[26:27], v[38:39]
	v_mul_f32_e32 v26, v31, v31
	v_mul_f32_e32 v27, v33, v33
	v_fmac_f32_e32 v26, v30, v30
	v_fmac_f32_e32 v27, v32, v32
	v_add_f32_e32 v26, v26, v27
	v_mul_f32_e32 v27, v29, v29
	v_mul_f32_e32 v36, v35, v35
	v_fmac_f32_e32 v27, v28, v28
	v_fmac_f32_e32 v36, v34, v34
	v_add_f32_e32 v27, v27, v36
	v_add_f32_e32 v38, v26, v27
	v_cvt_pk_bf16_f32 v26, v30, v31
	v_cvt_pk_bf16_f32 v27, v32, v33
	v_lshlrev_b32_e32 v30, 16, v74
	v_and_b32_e32 v31, 0xffff0000, v74
	v_lshlrev_b32_e32 v32, 16, v75
	v_and_b32_e32 v33, 0xffff0000, v75
	v_cvt_pk_bf16_f32 v28, v28, v29
	v_cvt_pk_bf16_f32 v29, v34, v35
	v_lshlrev_b32_e32 v34, 16, v76
	v_and_b32_e32 v35, 0xffff0000, v76
	v_pk_add_f32 v[24:25], v[24:25], v[32:33]
	v_pk_add_f32 v[22:23], v[22:23], v[30:31]
	v_lshlrev_b32_e32 v36, 16, v77
	v_and_b32_e32 v37, 0xffff0000, v77
	v_pk_add_f32 v[32:33], v[18:19], v[34:35]
	v_mul_f32_e32 v18, v23, v23
	v_mul_f32_e32 v19, v25, v25
	v_pk_add_f32 v[30:31], v[20:21], v[36:37]
	v_fmac_f32_e32 v18, v22, v22
	v_fmac_f32_e32 v19, v24, v24
	v_add_f32_e32 v18, v18, v19
	v_mul_f32_e32 v19, v33, v33
	v_mul_f32_e32 v20, v31, v31
	v_fmac_f32_e32 v19, v32, v32
	v_fmac_f32_e32 v20, v30, v30
	v_add_f32_e32 v19, v19, v20
	v_add_f32_e32 v18, v18, v19
	v_add_f32_e32 v21, v38, v18
	ds_bpermute_b32 v36, v196, v21
	v_lshl_add_u64 v[18:19], s[74:75], 0, v[96:97]
	v_lshl_add_u64 v[34:35], v[170:171], 1, v[18:19]
	global_store_dwordx4 v[34:35], v[26:29], off
	v_cvt_pk_bf16_f32 v20, v22, v23
	s_waitcnt lgkmcnt(0)
	v_add_f32_e32 v18, v21, v36
	ds_bpermute_b32 v19, v114, v18
	v_cvt_pk_bf16_f32 v21, v24, v25
	v_cvt_pk_bf16_f32 v22, v32, v33
	v_cvt_pk_bf16_f32 v23, v30, v31
	global_store_dwordx4 v[34:35], v[20:23], off offset:256
	s_and_saveexec_b64 s[28:29], s[4:5]
	s_cbranch_execz .LBB0_1113
	v_lshlrev_b64 v[20:21], 8, v[94:95]
	v_lshl_add_u64 v[20:21], s[10:11], 0, v[20:21]
	v_lshl_add_u64 v[20:21], s[26:27], 2, v[20:21]
	s_lshl_b32 s8, s39, 2
	v_lshl_add_u64 v[20:21], v[20:21], 0, s[8:9]
	s_waitcnt lgkmcnt(0)
	v_add_f32_e32 v18, v18, v19
	global_store_dword v[20:21], v18, off
.LBB0_1113:
	s_or_b64 exec, exec, s[28:29]
	v_lshlrev_b32_e32 v18, 16, v70
	s_waitcnt lgkmcnt(0)
	v_and_b32_e32 v19, 0xffff0000, v70
	v_lshlrev_b32_e32 v20, 16, v71
	v_and_b32_e32 v21, 0xffff0000, v71
	v_lshlrev_b32_e32 v22, 16, v72
	v_and_b32_e32 v23, 0xffff0000, v72
	v_lshlrev_b32_e32 v24, 16, v73
	v_and_b32_e32 v25, 0xffff0000, v73
	v_pk_add_f32 v[16:17], v[16:17], v[20:21]
	v_pk_add_f32 v[14:15], v[14:15], v[18:19]
	v_pk_add_f32 v[18:19], v[12:13], v[24:25]
	v_pk_add_f32 v[12:13], v[10:11], v[22:23]
	v_mul_f32_e32 v10, v15, v15
	v_mul_f32_e32 v11, v17, v17
	v_fmac_f32_e32 v10, v14, v14
	v_fmac_f32_e32 v11, v16, v16
	v_add_f32_e32 v10, v10, v11
	v_mul_f32_e32 v11, v13, v13
	v_mul_f32_e32 v20, v19, v19
	v_fmac_f32_e32 v11, v12, v12
	v_fmac_f32_e32 v20, v18, v18
	v_add_f32_e32 v11, v11, v20
	v_add_f32_e32 v22, v10, v11
	v_cvt_pk_bf16_f32 v10, v14, v15
	v_cvt_pk_bf16_f32 v11, v16, v17
	v_lshlrev_b32_e32 v14, 16, v66
	v_and_b32_e32 v15, 0xffff0000, v66
	v_lshlrev_b32_e32 v16, 16, v67
	v_and_b32_e32 v17, 0xffff0000, v67
	v_cvt_pk_bf16_f32 v12, v12, v13
	v_cvt_pk_bf16_f32 v13, v18, v19
	v_lshlrev_b32_e32 v18, 16, v68
	v_and_b32_e32 v19, 0xffff0000, v68
	v_pk_add_f32 v[8:9], v[8:9], v[16:17]
	v_pk_add_f32 v[6:7], v[6:7], v[14:15]
	v_lshlrev_b32_e32 v20, 16, v69
	v_and_b32_e32 v21, 0xffff0000, v69
	v_pk_add_f32 v[16:17], v[2:3], v[18:19]
	v_mul_f32_e32 v2, v7, v7
	v_mul_f32_e32 v3, v9, v9
	v_pk_add_f32 v[14:15], v[4:5], v[20:21]
	v_fmac_f32_e32 v2, v6, v6
	v_fmac_f32_e32 v3, v8, v8
	v_add_f32_e32 v2, v2, v3
	v_mul_f32_e32 v3, v17, v17
	v_mul_f32_e32 v4, v15, v15
	v_fmac_f32_e32 v3, v16, v16
	v_fmac_f32_e32 v4, v14, v14
	v_add_f32_e32 v3, v3, v4
	v_add_f32_e32 v2, v2, v3
	v_add_f32_e32 v5, v22, v2
	ds_bpermute_b32 v20, v196, v5
	v_lshl_add_u64 v[2:3], s[74:75], 0, v[92:93]
	v_lshl_add_u64 v[18:19], v[170:171], 1, v[2:3]
	global_store_dwordx4 v[18:19], v[10:13], off
	v_cvt_pk_bf16_f32 v4, v6, v7
	s_waitcnt lgkmcnt(0)
	v_add_f32_e32 v2, v5, v20
	ds_bpermute_b32 v3, v114, v2
	v_cvt_pk_bf16_f32 v5, v8, v9
	v_cvt_pk_bf16_f32 v6, v16, v17
	v_cvt_pk_bf16_f32 v7, v14, v15
	global_store_dwordx4 v[18:19], v[4:7], off offset:256
	s_and_saveexec_b64 s[28:29], s[4:5]
	s_cbranch_execz .LBB0_1115
	v_lshlrev_b64 v[4:5], 8, v[90:91]
	v_lshl_add_u64 v[4:5], s[10:11], 0, v[4:5]
	v_lshl_add_u64 v[4:5], s[26:27], 2, v[4:5]
	s_lshl_b32 s8, s39, 2
	v_lshl_add_u64 v[4:5], v[4:5], 0, s[8:9]
	s_waitcnt lgkmcnt(0)
	v_add_f32_e32 v2, v2, v3
	global_store_dword v[4:5], v2, off

; __device__ __forceinline__ unsigned cvt_pk_bf16(float lo, float hi) { unsigned r; asm volatile("v_cvt_pk_bf16_f32 %0, %1, %2" : "=v"(r) : "v"(lo), "v"(hi)); return r; }
; __device__ __forceinline__ float bflo(unsigned w) { return __uint_as_float(w << 16); }
; __device__ __forceinline__ float bfhi(unsigned w) { return __uint_as_float(w & 0xffff0000u); }
;     __device__ __forceinline__ void operator()(const f32x4 (&acc)[2][2][4][2], const Unit& u, int wr, int wc, int fr, int fq) const {
;         const int row0 = u.pm * BM + wr * 64 + fr, col0 = u.pn * BM + wc * 32 + 8 * fq;
; #pragma unroll
;         for (int ai = 0; ai < 2; ++ai) {
;             u32x4 bw[4][2];
; #pragma unroll
;             for (int m = 0; m < 4; ++m)
; #pragma unroll
;                 for (int bj = 0; bj < 2; ++bj) bw[m][bj] = *(const u32x4*)((const bf16_t*)base + (size_t)(row0 + ai * HALF + m * 16) * DM + col0 + bj * HALF);
; #pragma unroll
;             for (int m = 0; m < 4; ++m) { const int row = row0 + ai * HALF + m * 16; const size_t off = (size_t)row * DM + col0; float ss = 0.f;
; #pragma unroll
;                 for (int bj = 0; bj < 2; ++bj) { const u32x4 w = bw[m][bj];
;                     const f32x4 b0 = {bflo(w.x), bfhi(w.x), bflo(w.y), bfhi(w.y)}, b1 = {bflo(w.z), bfhi(w.z), bflo(w.w), bfhi(w.w)};
;                     const f32x4 o0 = b0 + acc[ai][bj][m][0], o1 = b1 + acc[ai][bj][m][1];
;                     ss += ((o0[0] * o0[0] + o0[1] * o0[1]) + (o0[2] * o0[2] + o0[3] * o0[3])) + ((o1[0] * o1[0] + o1[1] * o1[1]) + (o1[2] * o1[2] + o1[3] * o1[3]));
;                     u32x4 w2; w2.x = cvt_pk_bf16(o0[0], o0[1]); w2.y = cvt_pk_bf16(o0[2], o0[3]); w2.z = cvt_pk_bf16(o1[0], o1[1]); w2.w = cvt_pk_bf16(o1[2], o1[3]);
;                     *(u32x4*)(hout + off + bj * HALF) = w2; }
;                 ss += __shfl_xor(ss, 16); ss += __shfl_xor(ss, 32);
;                 if (fq == 0) part[(size_t)row * 64 + u.pn * 4 + wc] = ss; }
.LBB0_1312:
	v_lshl_or_b32 v170, s12, 8, v191
	v_lshl_add_u32 v174, s28, 8, v183
	v_ashrrev_i32_e32 v171, 31, v170
	v_lshlrev_b64 v[206:207], 1, v[170:171]
	v_ashrrev_i32_e32 v175, 31, v174
	v_lshl_add_u64 v[172:173], s[74:75], 0, v[206:207]
	v_lshlrev_b64 v[196:197], 13, v[174:175]
	v_lshl_add_u64 v[130:131], v[172:173], 0, v[196:197]
	global_load_dwordx4 v[198:201], v[130:131], off
	global_load_dwordx4 v[202:205], v[130:131], off offset:256
	v_or_b32_e32 v186, 16, v174
	v_or_b32_e32 v180, 32, v174
	v_or_b32_e32 v176, 48, v174
	v_ashrrev_i32_e32 v187, 31, v186
	v_ashrrev_i32_e32 v181, 31, v180
	v_ashrrev_i32_e32 v177, 31, v176
	v_lshlrev_b64 v[188:189], 13, v[186:187]
	v_lshlrev_b64 v[184:185], 13, v[180:181]
	v_lshlrev_b64 v[178:179], 13, v[176:177]
	v_lshl_add_u64 v[130:131], v[172:173], 0, v[188:189]
	v_lshl_add_u64 v[132:133], v[172:173], 0, v[184:185]
	v_lshl_add_u64 v[208:209], v[172:173], 0, v[178:179]
	global_load_dwordx4 v[150:153], v[130:131], off
	global_load_dwordx4 v[146:149], v[130:131], off offset:256
	global_load_dwordx4 v[142:145], v[132:133], off
	global_load_dwordx4 v[138:141], v[132:133], off offset:256
	global_load_dwordx4 v[134:137], v[208:209], off
	s_nop 0
	global_load_dwordx4 v[130:133], v[208:209], off offset:256
	v_add_u32_e32 v218, 0x80, v174
	v_ashrrev_i32_e32 v219, 31, v218
	v_lshlrev_b64 v[218:219], 13, v[218:219]
	v_lshl_add_u64 v[218:219], v[172:173], 0, v[218:219]
	global_load_dwordx4 v[220:223], v[218:219], off
	global_load_dwordx4 v[224:227], v[218:219], off offset:256
	v_add_co_u32_e32 v218, vcc, 0x20000, v218
	s_nop 1
	v_addc_co_u32_e32 v219, vcc, 0, v219, vcc
	global_load_dwordx4 v[228:231], v[218:219], off
	global_load_dwordx4 v[232:235], v[218:219], off offset:256
	v_add_co_u32_e32 v218, vcc, 0x20000, v218
	s_nop 1
	v_addc_co_u32_e32 v219, vcc, 0, v219, vcc
	global_load_dwordx4 v[236:239], v[218:219], off
	global_load_dwordx4 v[240:243], v[218:219], off offset:256
	v_add_co_u32_e32 v218, vcc, 0x20000, v218
	s_nop 1
	v_addc_co_u32_e32 v219, vcc, 0, v219, vcc
	global_load_dwordx4 v[244:247], v[218:219], off
	global_load_dwordx4 v[248:251], v[218:219], off offset:256
	v_and_b32_e32 v209, 64, v195
	v_xor_b32_e32 v208, 16, v195
	v_add_u32_e32 v209, 64, v209
	v_xor_b32_e32 v210, 32, v195
	v_cmp_lt_i32_e32 vcc, v208, v209
	s_lshl_b32 s8, s12, 2
	s_ashr_i32 s9, s8, 31
	v_cndmask_b32_e32 v211, v195, v208, vcc
	v_cmp_lt_i32_e32 vcc, v210, v209
	v_lshl_add_u64 v[208:209], s[74:75], 0, v[196:197]
	v_lshlrev_b32_e32 v196, 2, v211
	v_cndmask_b32_e32 v216, v195, v210, vcc
	v_lshl_add_u64 v[206:207], v[208:209], 0, v[206:207]
	s_waitcnt vmcnt(0)
	v_lshlrev_b32_e32 v208, 16, v198
	v_and_b32_e32 v209, 0xffff0000, v198
	v_lshlrev_b32_e32 v198, 16, v199
	v_and_b32_e32 v199, 0xffff0000, v199
	v_lshlrev_b32_e32 v210, 16, v200
	v_and_b32_e32 v211, 0xffff0000, v200
	v_lshlrev_b32_e32 v200, 16, v201
	v_and_b32_e32 v201, 0xffff0000, v201
	v_lshlrev_b32_e32 v212, 16, v202
	v_and_b32_e32 v213, 0xffff0000, v202
	v_lshlrev_b32_e32 v202, 16, v203
	v_and_b32_e32 v203, 0xffff0000, v203
	v_lshlrev_b32_e32 v214, 16, v204
	v_and_b32_e32 v215, 0xffff0000, v204
	v_lshlrev_b32_e32 v204, 16, v205
	v_and_b32_e32 v205, 0xffff0000, v205
	v_pk_add_f32 v[128:129], v[128:129], v[198:199]
	v_pk_add_f32 v[126:127], v[126:127], v[208:209]
	v_pk_add_f32 v[124:125], v[124:125], v[200:201]
	v_pk_add_f32 v[122:123], v[122:123], v[210:211]
	v_pk_add_f32 v[120:121], v[120:121], v[202:203]
	v_pk_add_f32 v[118:119], v[118:119], v[212:213]
	v_pk_add_f32 v[198:199], v[116:117], v[204:205]
	v_pk_add_f32 v[200:201], v[114:115], v[214:215]
	v_mul_f32_e32 v116, v127, v127
	v_mul_f32_e32 v117, v129, v129
	v_mul_f32_e32 v197, v123, v123
	v_mul_f32_e32 v202, v125, v125
	v_cvt_pk_bf16_f32 v114, v126, v127
	v_cvt_pk_bf16_f32 v115, v128, v129
	v_mul_f32_e32 v127, v119, v119
	v_mul_f32_e32 v129, v121, v121
	v_mul_f32_e32 v203, v201, v201
	v_mul_f32_e32 v204, v199, v199
	v_fmac_f32_e32 v116, v126, v126
	v_fmac_f32_e32 v117, v128, v128
	v_fmac_f32_e32 v197, v122, v122
	v_fmac_f32_e32 v202, v124, v124
	v_fmac_f32_e32 v127, v118, v118
	v_fmac_f32_e32 v129, v120, v120
	v_fmac_f32_e32 v203, v200, v200
	v_fmac_f32_e32 v204, v198, v198
	v_add_f32_e32 v116, v116, v117
	v_add_f32_e32 v117, v197, v202
	v_add_f32_e32 v126, v127, v129
	v_add_f32_e32 v127, v203, v204
	v_add_f32_e32 v116, v116, v117
	v_add_f32_e32 v117, v126, v127
	v_add_f32_e32 v126, v116, v117
	ds_bpermute_b32 v127, v196, v126
	v_cvt_pk_bf16_f32 v116, v122, v123
	v_cvt_pk_bf16_f32 v117, v124, v125
	global_store_dwordx4 v[206:207], v[114:117], off
	v_cvt_pk_bf16_f32 v118, v118, v119
	v_cvt_pk_bf16_f32 v119, v120, v121
	v_cvt_pk_bf16_f32 v120, v200, v201
	v_cvt_pk_bf16_f32 v121, v198, v199
	global_store_dwordx4 v[206:207], v[118:121], off offset:256
	s_waitcnt lgkmcnt(0)
	v_add_f32_e32 v115, v126, v127
	v_lshlrev_b32_e32 v114, 2, v216
	ds_bpermute_b32 v116, v114, v115
	s_and_saveexec_b64 s[28:29], s[4:5]
	s_cbranch_execz .LBB0_1314
	v_lshlrev_b64 v[118:119], 8, v[174:175]
	v_lshl_add_u64 v[118:119], s[10:11], 0, v[118:119]
	v_lshl_add_u64 v[118:119], s[8:9], 2, v[118:119]
	s_lshl_b32 s12, s39, 2
	v_lshl_add_u64 v[118:119], v[118:119], 0, s[12:13]
	s_waitcnt lgkmcnt(0)
	v_add_f32_e32 v115, v115, v116
	global_store_dword v[118:119], v115, off

; __device__ __forceinline__ unsigned cvt_pk_bf16(float lo, float hi) { unsigned r; asm volatile("v_cvt_pk_bf16_f32 %0, %1, %2" : "=v"(r) : "v"(lo), "v"(hi)); return r; }
; __device__ __forceinline__ float bflo(unsigned w) { return __uint_as_float(w << 16); }
; __device__ __forceinline__ float bfhi(unsigned w) { return __uint_as_float(w & 0xffff0000u); }
;     __device__ __forceinline__ void operator()(const f32x4 (&acc)[2][2][4][2], const Unit& u, int wr, int wc, int fr, int fq) const {
;     ...
;         for (int ai = 0; ai < 2; ++ai) {
;             u32x4 bw[4][2];
; #pragma unroll
;             for (int m = 0; m < 4; ++m)
; #pragma unroll
;                 for (int bj = 0; bj < 2; ++bj) bw[m][bj] = *(const u32x4*)((const bf16_t*)base + (size_t)(row0 + ai * HALF + m * 16) * DM + col0 + bj * HALF);
; #pragma unroll
;             for (int m = 0; m < 4; ++m) { const int row = row0 + ai * HALF + m * 16; const size_t off = (size_t)row * DM + col0; float ss = 0.f;
; #pragma unroll
;                 for (int bj = 0; bj < 2; ++bj) { const u32x4 w = bw[m][bj];
;                     const f32x4 b0 = {bflo(w.x), bfhi(w.x), bflo(w.y), bfhi(w.y)}, b1 = {bflo(w.z), bfhi(w.z), bflo(w.w), bfhi(w.w)};
;                     const f32x4 o0 = b0 + acc[ai][bj][m][0], o1 = b1 + acc[ai][bj][m][1];
;                     ss += ((o0[0] * o0[0] + o0[1] * o0[1]) + (o0[2] * o0[2] + o0[3] * o0[3])) + ((o1[0] * o1[0] + o1[1] * o1[1]) + (o1[2] * o1[2] + o1[3] * o1[3]));
;                     u32x4 w2; w2.x = cvt_pk_bf16(o0[0], o0[1]); w2.y = cvt_pk_bf16(o0[2], o0[3]); w2.z = cvt_pk_bf16(o1[0], o1[1]); w2.w = cvt_pk_bf16(o1[2], o1[3]);
;                     *(u32x4*)(hout + off + bj * HALF) = w2; }
;                 ss += __shfl_xor(ss, 16); ss += __shfl_xor(ss, 32);
;                 if (fq == 0) part[(size_t)row * 64 + u.pn * 4 + wc] = ss; }
.LBB0_1320:
	s_or_b64 exec, exec, s[28:29]
	v_add_u32_e32 v102, 0x80, v174
	v_ashrrev_i32_e32 v103, 31, v102
	v_lshlrev_b64 v[112:113], 13, v[102:103]
	s_waitcnt lgkmcnt(0)
	v_lshl_add_u64 v[66:67], v[172:173], 0, v[112:113]
	v_add_u32_e32 v98, 0x90, v174
	v_add_u32_e32 v94, 0xa0, v174
	v_add_u32_e32 v90, 0xb0, v174
	v_ashrrev_i32_e32 v99, 31, v98
	v_ashrrev_i32_e32 v95, 31, v94
	v_ashrrev_i32_e32 v91, 31, v90
	v_lshlrev_b64 v[100:101], 13, v[98:99]
	v_lshlrev_b64 v[96:97], 13, v[94:95]
	v_lshlrev_b64 v[92:93], 13, v[90:91]
	v_lshl_add_u64 v[66:67], v[172:173], 0, v[100:101]
	v_lshl_add_u64 v[68:69], v[172:173], 0, v[96:97]
	v_lshl_add_u64 v[116:117], v[172:173], 0, v[92:93]
	s_nop 0
	v_mov_b32_e32 v104, v220
	v_mov_b32_e32 v105, v221
	v_mov_b32_e32 v106, v222
	v_mov_b32_e32 v107, v223
	v_mov_b32_e32 v108, v224
	v_mov_b32_e32 v109, v225
	v_mov_b32_e32 v110, v226
	v_mov_b32_e32 v111, v227
	v_mov_b32_e32 v86, v228
	v_mov_b32_e32 v87, v229
	v_mov_b32_e32 v88, v230
	v_mov_b32_e32 v89, v231
	v_mov_b32_e32 v82, v232
	v_mov_b32_e32 v83, v233
	v_mov_b32_e32 v84, v234
	v_mov_b32_e32 v85, v235
	v_mov_b32_e32 v78, v236
	v_mov_b32_e32 v79, v237
	v_mov_b32_e32 v80, v238
	v_mov_b32_e32 v81, v239
	v_mov_b32_e32 v74, v240
	v_mov_b32_e32 v75, v241
	v_mov_b32_e32 v76, v242
	v_mov_b32_e32 v77, v243
	v_mov_b32_e32 v70, v244
	v_mov_b32_e32 v71, v245
	v_mov_b32_e32 v72, v246
	v_mov_b32_e32 v73, v247
	v_mov_b32_e32 v66, v248
	v_mov_b32_e32 v67, v249
	v_mov_b32_e32 v68, v250
	v_mov_b32_e32 v69, v251
	v_lshlrev_b32_e32 v116, 16, v104
	v_and_b32_e32 v117, 0xffff0000, v104
	v_lshlrev_b32_e32 v104, 16, v105
	v_and_b32_e32 v105, 0xffff0000, v105
	v_lshlrev_b32_e32 v118, 16, v106
	v_and_b32_e32 v119, 0xffff0000, v106
	v_lshlrev_b32_e32 v106, 16, v107
	v_and_b32_e32 v107, 0xffff0000, v107
	v_lshlrev_b32_e32 v120, 16, v108
	v_and_b32_e32 v121, 0xffff0000, v108
	v_lshlrev_b32_e32 v108, 16, v109
	v_and_b32_e32 v109, 0xffff0000, v109
	v_lshlrev_b32_e32 v122, 16, v110
	v_and_b32_e32 v123, 0xffff0000, v110
	v_lshlrev_b32_e32 v110, 16, v111
	v_and_b32_e32 v111, 0xffff0000, v111
	v_pk_add_f32 v[64:65], v[64:65], v[104:105]
	v_pk_add_f32 v[62:63], v[62:63], v[116:117]
	v_pk_add_f32 v[60:61], v[60:61], v[106:107]
	v_pk_add_f32 v[58:59], v[58:59], v[118:119]
	v_pk_add_f32 v[56:57], v[56:57], v[108:109]
	v_pk_add_f32 v[54:55], v[54:55], v[120:121]
	v_pk_add_f32 v[104:105], v[52:53], v[110:111]
	v_pk_add_f32 v[106:107], v[50:51], v[122:123]
	v_mul_f32_e32 v108, v63, v63
	v_mul_f32_e32 v109, v65, v65
	v_mul_f32_e32 v110, v59, v59
	v_mul_f32_e32 v111, v61, v61
	v_cvt_pk_bf16_f32 v50, v62, v63
	v_cvt_pk_bf16_f32 v51, v64, v65
	v_cvt_pk_bf16_f32 v52, v58, v59
	v_cvt_pk_bf16_f32 v53, v60, v61
	v_mul_f32_e32 v59, v55, v55
	v_mul_f32_e32 v61, v57, v57
	v_mul_f32_e32 v63, v107, v107
	v_mul_f32_e32 v65, v105, v105
	v_fmac_f32_e32 v108, v62, v62
	v_fmac_f32_e32 v109, v64, v64
	v_fmac_f32_e32 v110, v58, v58
	v_fmac_f32_e32 v111, v60, v60
	v_fmac_f32_e32 v59, v54, v54
	v_fmac_f32_e32 v61, v56, v56
	v_fmac_f32_e32 v63, v106, v106
	v_fmac_f32_e32 v65, v104, v104
	v_add_f32_e32 v58, v108, v109
	v_add_f32_e32 v60, v110, v111
	v_add_f32_e32 v59, v59, v61
	v_add_f32_e32 v61, v63, v65
	v_add_f32_e32 v58, v58, v60
	v_add_f32_e32 v59, v59, v61
	v_add_f32_e32 v60, v58, v59
	ds_bpermute_b32 v61, v196, v60
	v_lshl_add_u64 v[58:59], s[74:75], 0, v[112:113]
	v_lshl_add_u64 v[58:59], v[170:171], 1, v[58:59]
	global_store_dwordx4 v[58:59], v[50:53], off
	s_waitcnt lgkmcnt(0)
	s_nop 0
	v_add_f32_e32 v50, v60, v61
	ds_bpermute_b32 v51, v114, v50
	v_cvt_pk_bf16_f32 v52, v54, v55
	v_cvt_pk_bf16_f32 v53, v56, v57
	v_cvt_pk_bf16_f32 v54, v106, v107
	v_cvt_pk_bf16_f32 v55, v104, v105
	global_store_dwordx4 v[58:59], v[52:55], off offset:256
	s_and_saveexec_b64 s[28:29], s[4:5]
	s_cbranch_execz .LBB0_1322
	v_lshlrev_b64 v[52:53], 8, v[102:103]
	v_lshl_add_u64 v[52:53], s[10:11], 0, v[52:53]
	v_lshl_add_u64 v[52:53], s[8:9], 2, v[52:53]
	s_lshl_b32 s12, s39, 2
	v_lshl_add_u64 v[52:53], v[52:53], 0, s[12:13]
	s_waitcnt lgkmcnt(0)
	v_add_f32_e32 v50, v50, v51
	global_store_dword v[52:53], v50, off
.LBB0_1322:
	s_or_b64 exec, exec, s[28:29]
	v_lshlrev_b32_e32 v50, 16, v86
	s_waitcnt lgkmcnt(0)
	v_and_b32_e32 v51, 0xffff0000, v86
	v_lshlrev_b32_e32 v52, 16, v87
	v_and_b32_e32 v53, 0xffff0000, v87
	v_lshlrev_b32_e32 v54, 16, v88
	v_and_b32_e32 v55, 0xffff0000, v88
	v_lshlrev_b32_e32 v56, 16, v89
	v_and_b32_e32 v57, 0xffff0000, v89
	v_pk_add_f32 v[48:49], v[48:49], v[52:53]
	v_pk_add_f32 v[46:47], v[46:47], v[50:51]
	v_pk_add_f32 v[50:51], v[44:45], v[56:57]
	v_pk_add_f32 v[44:45], v[42:43], v[54:55]
	v_mul_f32_e32 v42, v47, v47
	v_mul_f32_e32 v43, v49, v49
	v_fmac_f32_e32 v42, v46, v46
	v_fmac_f32_e32 v43, v48, v48
	v_add_f32_e32 v42, v42, v43
	v_mul_f32_e32 v43, v45, v45
	v_mul_f32_e32 v52, v51, v51
	v_fmac_f32_e32 v43, v44, v44
	v_fmac_f32_e32 v52, v50, v50
	v_add_f32_e32 v43, v43, v52
	v_add_f32_e32 v54, v42, v43
	v_cvt_pk_bf16_f32 v42, v46, v47
	v_cvt_pk_bf16_f32 v43, v48, v49
	v_lshlrev_b32_e32 v46, 16, v82
	v_and_b32_e32 v47, 0xffff0000, v82
	v_lshlrev_b32_e32 v48, 16, v83
	v_and_b32_e32 v49, 0xffff0000, v83
	v_cvt_pk_bf16_f32 v44, v44, v45
	v_cvt_pk_bf16_f32 v45, v50, v51
	v_lshlrev_b32_e32 v50, 16, v84
	v_and_b32_e32 v51, 0xffff0000, v84
	v_pk_add_f32 v[40:41], v[40:41], v[48:49]
	v_pk_add_f32 v[38:39], v[38:39], v[46:47]
	v_lshlrev_b32_e32 v52, 16, v85
	v_and_b32_e32 v53, 0xffff0000, v85
	v_pk_add_f32 v[48:49], v[34:35], v[50:51]
	v_mul_f32_e32 v34, v39, v39
	v_mul_f32_e32 v35, v41, v41
	v_pk_add_f32 v[46:47], v[36:37], v[52:53]
	v_fmac_f32_e32 v34, v38, v38
	v_fmac_f32_e32 v35, v40, v40
	v_add_f32_e32 v34, v34, v35
	v_mul_f32_e32 v35, v49, v49
	v_mul_f32_e32 v36, v47, v47
	v_fmac_f32_e32 v35, v48, v48
	v_fmac_f32_e32 v36, v46, v46
	v_add_f32_e32 v35, v35, v36
	v_add_f32_e32 v34, v34, v35
	v_add_f32_e32 v37, v54, v34
	ds_bpermute_b32 v52, v196, v37
	v_lshl_add_u64 v[34:35], s[74:75], 0, v[100:101]
	v_lshl_add_u64 v[50:51], v[170:171], 1, v[34:35]
	global_store_dwordx4 v[50:51], v[42:45], off
	v_cvt_pk_bf16_f32 v36, v38, v39
	s_waitcnt lgkmcnt(0)
	v_add_f32_e32 v34, v37, v52
	ds_bpermute_b32 v35, v114, v34
	v_cvt_pk_bf16_f32 v37, v40, v41
	v_cvt_pk_bf16_f32 v38, v48, v49
	v_cvt_pk_bf16_f32 v39, v46, v47
	global_store_dwordx4 v[50:51], v[36:39], off offset:256
	s_and_saveexec_b64 s[28:29], s[4:5]
	s_cbranch_execz .LBB0_1324
	v_lshlrev_b64 v[36:37], 8, v[98:99]
	v_lshl_add_u64 v[36:37], s[10:11], 0, v[36:37]
	v_lshl_add_u64 v[36:37], s[8:9], 2, v[36:37]
	s_lshl_b32 s12, s39, 2
	v_lshl_add_u64 v[36:37], v[36:37], 0, s[12:13]
	s_waitcnt lgkmcnt(0)
	v_add_f32_e32 v34, v34, v35
	global_store_dword v[36:37], v34, off
; __device__ __forceinline__ unsigned cvt_pk_bf16(float lo, float hi) { unsigned r; asm volatile("v_cvt_pk_bf16_f32 %0, %1, %2" : "=v"(r) : "v"(lo), "v"(hi)); return r; }
; __device__ __forceinline__ float bflo(unsigned w) { return __uint_as_float(w << 16); }
; __device__ __forceinline__ float bfhi(unsigned w) { return __uint_as_float(w & 0xffff0000u); }
;     __device__ __forceinline__ void operator()(const f32x4 (&acc)[2][2][4][2], const Unit& u, int wr, int wc, int fr, int fq) const {
;     ...
;         for (int ai = 0; ai < 2; ++ai) {
;             u32x4 bw[4][2];
; #pragma unroll
;             for (int m = 0; m < 4; ++m)
; #pragma unroll
;                 for (int bj = 0; bj < 2; ++bj) bw[m][bj] = *(const u32x4*)((const bf16_t*)base + (size_t)(row0 + ai * HALF + m * 16) * DM + col0 + bj * HALF);
; #pragma unroll
;             for (int m = 0; m < 4; ++m) { const int row = row0 + ai * HALF + m * 16; const size_t off = (size_t)row * DM + col0; float ss = 0.f;
; #pragma unroll
;                 for (int bj = 0; bj < 2; ++bj) { const u32x4 w = bw[m][bj];
;                     const f32x4 b0 = {bflo(w.x), bfhi(w.x), bflo(w.y), bfhi(w.y)}, b1 = {bflo(w.z), bfhi(w.z), bflo(w.w), bfhi(w.w)};
;                     const f32x4 o0 = b0 + acc[ai][bj][m][0], o1 = b1 + acc[ai][bj][m][1];
;                     ss += ((o0[0] * o0[0] + o0[1] * o0[1]) + (o0[2] * o0[2] + o0[3] * o0[3])) + ((o1[0] * o1[0] + o1[1] * o1[1]) + (o1[2] * o1[2] + o1[3] * o1[3]));
;                     u32x4 w2; w2.x = cvt_pk_bf16(o0[0], o0[1]); w2.y = cvt_pk_bf16(o0[2], o0[3]); w2.z = cvt_pk_bf16(o1[0], o1[1]); w2.w = cvt_pk_bf16(o1[2], o1[3]);
;                     *(u32x4*)(hout + off + bj * HALF) = w2; }
;                 ss += __shfl_xor(ss, 16); ss += __shfl_xor(ss, 32);
;                 if (fq == 0) part[(size_t)row * 64 + u.pn * 4 + wc] = ss; }
.LBB0_1324:
	s_or_b64 exec, exec, s[28:29]
	v_lshlrev_b32_e32 v34, 16, v78
	s_waitcnt lgkmcnt(0)
	v_and_b32_e32 v35, 0xffff0000, v78
	v_lshlrev_b32_e32 v36, 16, v79
	v_and_b32_e32 v37, 0xffff0000, v79
	v_lshlrev_b32_e32 v38, 16, v80
	v_and_b32_e32 v39, 0xffff0000, v80
	v_lshlrev_b32_e32 v40, 16, v81
	v_and_b32_e32 v41, 0xffff0000, v81
	v_pk_add_f32 v[32:33], v[32:33], v[36:37]
	v_pk_add_f32 v[30:31], v[30:31], v[34:35]
	v_pk_add_f32 v[34:35], v[28:29], v[40:41]
	v_pk_add_f32 v[28:29], v[26:27], v[38:39]
	v_mul_f32_e32 v26, v31, v31
	v_mul_f32_e32 v27, v33, v33
	v_fmac_f32_e32 v26, v30, v30
	v_fmac_f32_e32 v27, v32, v32
	v_add_f32_e32 v26, v26, v27
	v_mul_f32_e32 v27, v29, v29
	v_mul_f32_e32 v36, v35, v35
	v_fmac_f32_e32 v27, v28, v28
	v_fmac_f32_e32 v36, v34, v34
	v_add_f32_e32 v27, v27, v36
	v_add_f32_e32 v38, v26, v27
	v_cvt_pk_bf16_f32 v26, v30, v31
	v_cvt_pk_bf16_f32 v27, v32, v33
	v_lshlrev_b32_e32 v30, 16, v74
	v_and_b32_e32 v31, 0xffff0000, v74
	v_lshlrev_b32_e32 v32, 16, v75
	v_and_b32_e32 v33, 0xffff0000, v75
	v_cvt_pk_bf16_f32 v28, v28, v29
	v_cvt_pk_bf16_f32 v29, v34, v35
	v_lshlrev_b32_e32 v34, 16, v76
	v_and_b32_e32 v35, 0xffff0000, v76
	v_pk_add_f32 v[24:25], v[24:25], v[32:33]
	v_pk_add_f32 v[22:23], v[22:23], v[30:31]
	v_lshlrev_b32_e32 v36, 16, v77
	v_and_b32_e32 v37, 0xffff0000, v77
	v_pk_add_f32 v[32:33], v[18:19], v[34:35]
	v_mul_f32_e32 v18, v23, v23
	v_mul_f32_e32 v19, v25, v25
	v_pk_add_f32 v[30:31], v[20:21], v[36:37]
	v_fmac_f32_e32 v18, v22, v22
	v_fmac_f32_e32 v19, v24, v24
	v_add_f32_e32 v18, v18, v19
	v_mul_f32_e32 v19, v33, v33
	v_mul_f32_e32 v20, v31, v31
	v_fmac_f32_e32 v19, v32, v32
	v_fmac_f32_e32 v20, v30, v30
	v_add_f32_e32 v19, v19, v20
	v_add_f32_e32 v18, v18, v19
	v_add_f32_e32 v21, v38, v18
	ds_bpermute_b32 v36, v196, v21
	v_lshl_add_u64 v[18:19], s[74:75], 0, v[96:97]
	v_lshl_add_u64 v[34:35], v[170:171], 1, v[18:19]
	global_store_dwordx4 v[34:35], v[26:29], off
	v_cvt_pk_bf16_f32 v20, v22, v23
	s_waitcnt lgkmcnt(0)
	v_add_f32_e32 v18, v21, v36
	ds_bpermute_b32 v19, v114, v18
	v_cvt_pk_bf16_f32 v21, v24, v25
	v_cvt_pk_bf16_f32 v22, v32, v33
	v_cvt_pk_bf16_f32 v23, v30, v31
	global_store_dwordx4 v[34:35], v[20:23], off offset:256
	s_and_saveexec_b64 s[28:29], s[4:5]
	s_cbranch_execz .LBB0_1326
	v_lshlrev_b64 v[20:21], 8, v[94:95]
	v_lshl_add_u64 v[20:21], s[10:11], 0, v[20:21]
	v_lshl_add_u64 v[20:21], s[8:9], 2, v[20:21]
	s_lshl_b32 s12, s39, 2
	v_lshl_add_u64 v[20:21], v[20:21], 0, s[12:13]
	s_waitcnt lgkmcnt(0)
	v_add_f32_e32 v18, v18, v19
	global_store_dword v[20:21], v18, off
.LBB0_1326:
	s_or_b64 exec, exec, s[28:29]
	v_lshlrev_b32_e32 v18, 16, v70
	s_waitcnt lgkmcnt(0)
	v_and_b32_e32 v19, 0xffff0000, v70
	v_lshlrev_b32_e32 v20, 16, v71
	v_and_b32_e32 v21, 0xffff0000, v71
	v_lshlrev_b32_e32 v22, 16, v72
	v_and_b32_e32 v23, 0xffff0000, v72
	v_lshlrev_b32_e32 v24, 16, v73
	v_and_b32_e32 v25, 0xffff0000, v73
	v_pk_add_f32 v[16:17], v[16:17], v[20:21]
	v_pk_add_f32 v[14:15], v[14:15], v[18:19]
	v_pk_add_f32 v[18:19], v[12:13], v[24:25]
	v_pk_add_f32 v[12:13], v[10:11], v[22:23]
	v_mul_f32_e32 v10, v15, v15
	v_mul_f32_e32 v11, v17, v17
	v_fmac_f32_e32 v10, v14, v14
	v_fmac_f32_e32 v11, v16, v16
	v_add_f32_e32 v10, v10, v11
	v_mul_f32_e32 v11, v13, v13
	v_mul_f32_e32 v20, v19, v19
	v_fmac_f32_e32 v11, v12, v12
	v_fmac_f32_e32 v20, v18, v18
	v_add_f32_e32 v11, v11, v20
	v_add_f32_e32 v22, v10, v11
	v_cvt_pk_bf16_f32 v10, v14, v15
	v_cvt_pk_bf16_f32 v11, v16, v17
	v_lshlrev_b32_e32 v14, 16, v66
	v_and_b32_e32 v15, 0xffff0000, v66
	v_lshlrev_b32_e32 v16, 16, v67
	v_and_b32_e32 v17, 0xffff0000, v67
	v_cvt_pk_bf16_f32 v12, v12, v13
	v_cvt_pk_bf16_f32 v13, v18, v19
	v_lshlrev_b32_e32 v18, 16, v68
	v_and_b32_e32 v19, 0xffff0000, v68
	v_pk_add_f32 v[8:9], v[8:9], v[16:17]
	v_pk_add_f32 v[6:7], v[6:7], v[14:15]
	v_lshlrev_b32_e32 v20, 16, v69
	v_and_b32_e32 v21, 0xffff0000, v69
	v_pk_add_f32 v[16:17], v[2:3], v[18:19]
	v_mul_f32_e32 v2, v7, v7
	v_mul_f32_e32 v3, v9, v9
	v_pk_add_f32 v[14:15], v[4:5], v[20:21]
	v_fmac_f32_e32 v2, v6, v6
	v_fmac_f32_e32 v3, v8, v8
	v_add_f32_e32 v2, v2, v3
	v_mul_f32_e32 v3, v17, v17
	v_mul_f32_e32 v4, v15, v15
	v_fmac_f32_e32 v3, v16, v16
	v_fmac_f32_e32 v4, v14, v14
	v_add_f32_e32 v3, v3, v4
	v_add_f32_e32 v2, v2, v3
	v_add_f32_e32 v5, v22, v2
	ds_bpermute_b32 v20, v196, v5
	v_lshl_add_u64 v[2:3], s[74:75], 0, v[92:93]
	v_lshl_add_u64 v[18:19], v[170:171], 1, v[2:3]
	global_store_dwordx4 v[18:19], v[10:13], off
	v_cvt_pk_bf16_f32 v4, v6, v7
	s_waitcnt lgkmcnt(0)
	v_add_f32_e32 v2, v5, v20
	ds_bpermute_b32 v3, v114, v2
	v_cvt_pk_bf16_f32 v5, v8, v9
	v_cvt_pk_bf16_f32 v6, v16, v17
	v_cvt_pk_bf16_f32 v7, v14, v15
	global_store_dwordx4 v[18:19], v[4:7], off offset:256
	s_and_saveexec_b64 s[28:29], s[4:5]
	s_cbranch_execz .LBB0_1328
	v_lshlrev_b64 v[4:5], 8, v[90:91]
	v_lshl_add_u64 v[4:5], s[10:11], 0, v[4:5]
	v_lshl_add_u64 v[4:5], s[8:9], 2, v[4:5]
	s_lshl_b32 s12, s39, 2
	v_lshl_add_u64 v[4:5], v[4:5], 0, s[12:13]
	s_waitcnt lgkmcnt(0)
	v_add_f32_e32 v2, v2, v3
	global_store_dword v[4:5], v2, off
